# v58 + gate/up SwiGLU epilogue: scalar (x*-log2e) and (1+e) pairs packed into v_pk_mul_f32 / v_pk_add_f32 (56 fewer VALU per tile-wave)
# baseline (speedup 1.0000x reference)
; __device__ __forceinline__ unsigned pk_bf16(float lo, float hi) { f32x2 v = {lo, hi}; bf16x2_t b = __builtin_convertvector(v, bf16x2_t); return __builtin_bit_cast(unsigned, b); }
;     __device__ __forceinline__ void operator()(const f32x4 (&acc)[2][2][4][2], const Unit& u, int wr, int wc, int fr, int fq) const {
;         const int row0 = u.pm * BM + wr * 64 + fr; const int col0 = u.pn * HALF + wc * 32 + 8 * fq;
;         const float* bp = bias + (size_t)((u.pm * BM) >> 14) * 5632 + u.pn * BM + wc * 32 + 8 * fq;
;         f32x4 bz[2][2];
; #pragma unroll
;         for (int bj = 0; bj < 2; ++bj)
; #pragma unroll
;             for (int n = 0; n < 2; ++n) bz[bj][n] = *(const f32x4*)(bp + bj * HALF + 4 * n);
; #pragma unroll
;         for (int ai = 0; ai < 2; ++ai)
; #pragma unroll
;             for (int m = 0; m < 4; ++m) {
;                 float o[8]; const float rv = rsqrtf(rowss[row0 + ai * HALF + m * 16] * (1.0f / 1024.0f) + 1e-6f);
; #pragma unroll
;                 for (int n = 0; n < 2; ++n)
; #pragma unroll
;                     for (int j = 0; j < 4; ++j) { const float g = acc[ai][0][m][n][j] * rv + bz[0][n][j], up = acc[ai][1][m][n][j] * rv + bz[1][n][j];
;                         o[4 * n + j] = g * __builtin_amdgcn_rcpf(1.0f + __expf(-g)) * up; }
;                 u32x4 w; w.x = pk_bf16(o[0], o[1]); w.y = pk_bf16(o[2], o[3]); w.z = pk_bf16(o[4], o[5]); w.w = pk_bf16(o[6], o[7]);
;                 *(u32x4*)(act + (size_t)(row0 + ai * HALF + m * 16) * 2816 + col0) = w;
.LBB0_907:
	s_ashr_i32 s4, s34, 6
	s_mul_hi_i32 s5, s4, 0x5800
	s_mulk_i32 s4, 0x5800
	v_lshl_add_u32 v156, s34, 8, v162
	s_add_u32 s34, s14, s4
	s_addc_u32 s37, s15, s5
	s_lshl_b32 s4, s31, 8
	s_ashr_i32 s5, s4, 31
	s_lshl_b64 s[4:5], s[4:5], 2
	s_add_u32 s4, s34, s4
	s_addc_u32 s5, s37, s5
	s_add_u32 s4, s4, s30
	v_ashrrev_i32_e32 v157, 31, v156
	s_addc_u32 s5, s5, 0
	v_lshl_add_u64 v[158:159], v[156:157], 2, s[42:43]
	v_lshl_or_b32 v160, s31, 7, v164
	v_ashrrev_i32_e32 v161, 31, v160
	s_movk_i32 s12, 0x1600
	s_mov_b32 s100, 0xbfb8aa3b
	s_mov_b64 s[54:55], -1
	s_waitcnt vmcnt(8)
	v_fmamk_f32 v157, v147, 0x3a800000, v227
	s_nop 0
	v_rsq_f32_e32 v157, v157
	s_nop 0
	v_mov_b32_e32 v168, v157
	v_pk_fma_f32 v[142:143], v[142:143], v[168:169], v[246:247] op_sel_hi:[1,0,1]
	v_pk_fma_f32 v[134:135], v[134:135], v[168:169], v[238:239] op_sel_hi:[1,0,1]
	v_mul_f32_e32 v157, 0xbfb8aa3b, v142
	v_exp_f32_e32 v157, v157
	v_pk_fma_f32 v[136:137], v[136:137], v[168:169], v[240:241] op_sel_hi:[1,0,1]
	v_pk_fma_f32 v[138:139], v[138:139], v[168:169], v[242:243] op_sel_hi:[1,0,1]
	v_pk_fma_f32 v[130:131], v[130:131], v[168:169], v[174:175] op_sel_hi:[1,0,1]
	v_add_f32_e32 v157, 1.0, v157
	v_rcp_f32_e32 v170, v157
	v_mul_f32_e32 v157, 0xbfb8aa3b, v143
	v_exp_f32_e32 v157, v157
	v_pk_fma_f32 v[132:133], v[132:133], v[168:169], v[176:177] op_sel_hi:[1,0,1]
	v_add_f32_e32 v157, 1.0, v157
	v_rcp_f32_e32 v171, v157
	s_nop 0
	v_pk_mul_f32 v[142:143], v[142:143], v[170:171]
	s_nop 0
	v_pk_mul_f32 v[134:135], v[134:135], v[142:143]
	v_pk_fma_f32 v[142:143], v[144:145], v[168:169], v[248:249] op_sel_hi:[1,0,1]
	s_nop 0
	v_pk_mul_f32 v[144:145], v[142:143], s[100:101] op_sel_hi:[1,0]
	s_nop 0
	v_exp_f32_e32 v144, v144
	v_exp_f32_e32 v145, v145
	s_nop 0
	v_pk_add_f32 v[144:145], v[144:145], 1.0 op_sel_hi:[1,0]
	s_nop 0
	v_rcp_f32_e32 v144, v144
	v_rcp_f32_e32 v145, v145
	s_nop 0
	v_pk_mul_f32 v[142:143], v[142:143], v[144:145]
	s_nop 0
	v_pk_mul_f32 v[136:137], v[136:137], v[142:143]
	v_pk_mul_f32 v[142:143], v[138:139], s[100:101] op_sel_hi:[1,0]
	s_nop 0
	v_exp_f32_e32 v142, v142
	v_exp_f32_e32 v143, v143
	s_nop 0
	v_pk_add_f32 v[142:143], v[142:143], 1.0 op_sel_hi:[1,0]
	s_nop 0
	v_rcp_f32_e32 v142, v142
	v_rcp_f32_e32 v143, v143
	s_nop 0
	v_pk_mul_f32 v[138:139], v[138:139], v[142:143]
	s_nop 0
	v_pk_mul_f32 v[138:139], v[130:131], v[138:139]
	v_pk_fma_f32 v[130:131], v[140:141], v[168:169], v[244:245] op_sel_hi:[1,0,1]
	s_nop 0
	v_pk_mul_f32 v[140:141], v[130:131], s[100:101] op_sel_hi:[1,0]
	s_nop 0
	v_exp_f32_e32 v140, v140
	v_exp_f32_e32 v141, v141
	s_nop 0
	v_pk_add_f32 v[140:141], v[140:141], 1.0 op_sel_hi:[1,0]
	s_nop 0
	v_rcp_f32_e32 v140, v140
	v_rcp_f32_e32 v141, v141
	s_nop 0
	v_pk_mul_f32 v[130:131], v[130:131], v[140:141]
	s_nop 0
	v_pk_mul_f32 v[140:141], v[132:133], v[130:131]
	v_cvt_pk_bf16_f32 v130, v134, v135
	v_mov_b64_e32 v[134:135], s[2:3]
	v_cvt_pk_bf16_f32 v131, v136, v137
	v_cvt_pk_bf16_f32 v132, v138, v139
	v_mad_i64_i32 v[138:139], s[4:5], v156, s12, v[134:135]
	v_lshlrev_b64 v[136:137], 1, v[160:161]
	v_cvt_pk_bf16_f32 v133, v140, v141
	s_mov_b32 s99, 0
	v_lshl_add_u64 v[194:195], v[138:139], 0, v[136:137]
	global_store_dwordx4 v[194:195], v[130:133], off
	s_nop 1
	v_fmamk_f32 v131, v149, 0x3a800000, v227
	s_nop 0
	v_rsq_f32_e32 v131, v131
	s_nop 0
	v_mov_b32_e32 v132, v131
	v_pk_fma_f32 v[124:125], v[124:125], v[132:133], v[246:247] op_sel_hi:[1,0,1]
	v_pk_fma_f32 v[116:117], v[116:117], v[132:133], v[238:239] op_sel_hi:[1,0,1]
	v_mul_f32_e32 v131, 0xbfb8aa3b, v124
	v_exp_f32_e32 v131, v131
	v_pk_fma_f32 v[118:119], v[118:119], v[132:133], v[240:241] op_sel_hi:[1,0,1]
	v_pk_fma_f32 v[120:121], v[120:121], v[132:133], v[242:243] op_sel_hi:[1,0,1]
	v_pk_fma_f32 v[112:113], v[112:113], v[132:133], v[174:175] op_sel_hi:[1,0,1]
	v_add_f32_e32 v131, 1.0, v131
	v_rcp_f32_e32 v138, v131
	v_mul_f32_e32 v131, 0xbfb8aa3b, v125
	v_exp_f32_e32 v131, v131
	v_pk_fma_f32 v[114:115], v[114:115], v[132:133], v[176:177] op_sel_hi:[1,0,1]
	v_add_f32_e32 v131, 1.0, v131
	v_rcp_f32_e32 v139, v131
	s_nop 0
	v_pk_mul_f32 v[124:125], v[124:125], v[138:139]
	s_nop 0
	v_pk_mul_f32 v[116:117], v[116:117], v[124:125]
	v_pk_fma_f32 v[124:125], v[126:127], v[132:133], v[248:249] op_sel_hi:[1,0,1]
	s_nop 0
	v_pk_mul_f32 v[126:127], v[124:125], s[100:101] op_sel_hi:[1,0]
	s_nop 0
	v_exp_f32_e32 v126, v126
	v_exp_f32_e32 v127, v127
	s_nop 0
	v_pk_add_f32 v[126:127], v[126:127], 1.0 op_sel_hi:[1,0]
	s_nop 0
	v_rcp_f32_e32 v126, v126
	v_rcp_f32_e32 v127, v127
	s_nop 0
	v_pk_mul_f32 v[124:125], v[124:125], v[126:127]
	s_nop 0
	v_pk_mul_f32 v[118:119], v[118:119], v[124:125]
	v_pk_mul_f32 v[124:125], v[120:121], s[100:101] op_sel_hi:[1,0]
	s_nop 0
	v_exp_f32_e32 v124, v124
	v_exp_f32_e32 v125, v125
	s_nop 0
	v_pk_add_f32 v[124:125], v[124:125], 1.0 op_sel_hi:[1,0]
	s_nop 0
	v_rcp_f32_e32 v124, v124
	v_rcp_f32_e32 v125, v125
	s_nop 0
	v_pk_mul_f32 v[120:121], v[120:121], v[124:125]
	s_nop 0
	v_pk_mul_f32 v[120:121], v[112:113], v[120:121]
	v_pk_fma_f32 v[112:113], v[122:123], v[132:133], v[244:245] op_sel_hi:[1,0,1]
	s_nop 0
	v_pk_mul_f32 v[122:123], v[112:113], s[100:101] op_sel_hi:[1,0]
	s_nop 0
	v_exp_f32_e32 v122, v122
	v_exp_f32_e32 v123, v123
	s_nop 0
	v_pk_add_f32 v[122:123], v[122:123], 1.0 op_sel_hi:[1,0]
	s_nop 0
	v_rcp_f32_e32 v122, v122
	v_rcp_f32_e32 v123, v123
	s_nop 0
	v_pk_mul_f32 v[112:113], v[112:113], v[122:123]
	s_nop 0
	v_pk_mul_f32 v[122:123], v[114:115], v[112:113]
	v_cvt_pk_bf16_f32 v112, v116, v117
	s_mov_b32 s98, 0x16000
	v_cvt_pk_bf16_f32 v113, v118, v119
	v_cvt_pk_bf16_f32 v114, v120, v121
	v_cvt_pk_bf16_f32 v115, v122, v123
; __device__ __forceinline__ unsigned pk_bf16(float lo, float hi) { f32x2 v = {lo, hi}; bf16x2_t b = __builtin_convertvector(v, bf16x2_t); return __builtin_bit_cast(unsigned, b); }
;     __device__ __forceinline__ void operator()(const f32x4 (&acc)[2][2][4][2], const Unit& u, int wr, int wc, int fr, int fq) const {
;     ...
;             for (int m = 0; m < 4; ++m) {
;                 float o[8]; const float rv = rsqrtf(rowss[row0 + ai * HALF + m * 16] * (1.0f / 1024.0f) + 1e-6f);
; #pragma unroll
;                 for (int n = 0; n < 2; ++n)
; #pragma unroll
;                     for (int j = 0; j < 4; ++j) { const float g = acc[ai][0][m][n][j] * rv + bz[0][n][j], up = acc[ai][1][m][n][j] * rv + bz[1][n][j];
;                         o[4 * n + j] = g * __builtin_amdgcn_rcpf(1.0f + __expf(-g)) * up; }
;                 u32x4 w; w.x = pk_bf16(o[0], o[1]); w.y = pk_bf16(o[2], o[3]); w.z = pk_bf16(o[4], o[5]); w.w = pk_bf16(o[6], o[7]);
;                 *(u32x4*)(act + (size_t)(row0 + ai * HALF + m * 16) * 2816 + col0) = w;
	v_lshl_add_u64 v[116:117], v[194:195], 0, s[98:99]
	global_store_dwordx4 v[116:117], v[112:115], off
	s_nop 1
	v_fmamk_f32 v113, v151, 0x3a800000, v227
	s_nop 0
	v_rsq_f32_e32 v113, v113
	s_nop 0
	v_mov_b32_e32 v114, v113
	v_pk_fma_f32 v[108:109], v[108:109], v[114:115], v[246:247] op_sel_hi:[1,0,1]
	v_pk_fma_f32 v[100:101], v[100:101], v[114:115], v[238:239] op_sel_hi:[1,0,1]
	v_mul_f32_e32 v113, 0xbfb8aa3b, v108
	v_exp_f32_e32 v113, v113
	v_pk_fma_f32 v[102:103], v[102:103], v[114:115], v[240:241] op_sel_hi:[1,0,1]
	v_pk_fma_f32 v[104:105], v[104:105], v[114:115], v[242:243] op_sel_hi:[1,0,1]
	v_pk_fma_f32 v[96:97], v[96:97], v[114:115], v[174:175] op_sel_hi:[1,0,1]
	v_add_f32_e32 v113, 1.0, v113
	v_rcp_f32_e32 v116, v113
	v_mul_f32_e32 v113, 0xbfb8aa3b, v109
	v_exp_f32_e32 v113, v113
	v_pk_fma_f32 v[98:99], v[98:99], v[114:115], v[176:177] op_sel_hi:[1,0,1]
	v_add_f32_e32 v113, 1.0, v113
	v_rcp_f32_e32 v117, v113
	s_nop 0
	v_pk_mul_f32 v[108:109], v[108:109], v[116:117]
	s_nop 0
	v_pk_mul_f32 v[100:101], v[100:101], v[108:109]
	v_pk_fma_f32 v[108:109], v[110:111], v[114:115], v[248:249] op_sel_hi:[1,0,1]
	s_nop 0
	v_pk_mul_f32 v[110:111], v[108:109], s[100:101] op_sel_hi:[1,0]
	s_nop 0
	v_exp_f32_e32 v110, v110
	v_exp_f32_e32 v111, v111
	s_nop 0
	v_pk_add_f32 v[110:111], v[110:111], 1.0 op_sel_hi:[1,0]
	s_nop 0
	v_rcp_f32_e32 v110, v110
	v_rcp_f32_e32 v111, v111
	s_nop 0
	v_pk_mul_f32 v[108:109], v[108:109], v[110:111]
	s_nop 0
	v_pk_mul_f32 v[102:103], v[102:103], v[108:109]
	v_pk_mul_f32 v[108:109], v[104:105], s[100:101] op_sel_hi:[1,0]
	s_nop 0
	v_exp_f32_e32 v108, v108
	v_exp_f32_e32 v109, v109
	s_nop 0
	v_pk_add_f32 v[108:109], v[108:109], 1.0 op_sel_hi:[1,0]
	s_nop 0
	v_rcp_f32_e32 v108, v108
	v_rcp_f32_e32 v109, v109
	s_nop 0
	v_pk_mul_f32 v[104:105], v[104:105], v[108:109]
	s_nop 0
	v_pk_mul_f32 v[104:105], v[96:97], v[104:105]
	v_pk_fma_f32 v[96:97], v[106:107], v[114:115], v[244:245] op_sel_hi:[1,0,1]
	s_nop 0
	v_pk_mul_f32 v[106:107], v[96:97], s[100:101] op_sel_hi:[1,0]
	s_nop 0
	v_exp_f32_e32 v106, v106
	v_exp_f32_e32 v107, v107
	s_nop 0
	v_pk_add_f32 v[106:107], v[106:107], 1.0 op_sel_hi:[1,0]
	s_nop 0
	v_rcp_f32_e32 v106, v106
	v_rcp_f32_e32 v107, v107
	s_nop 0
	v_pk_mul_f32 v[96:97], v[96:97], v[106:107]
	s_nop 0
	v_pk_mul_f32 v[106:107], v[98:99], v[96:97]
	v_cvt_pk_bf16_f32 v96, v100, v101
	s_mov_b32 s98, 0x2c000
	v_cvt_pk_bf16_f32 v97, v102, v103
	v_cvt_pk_bf16_f32 v98, v104, v105
	v_cvt_pk_bf16_f32 v99, v106, v107
	v_lshl_add_u64 v[100:101], v[194:195], 0, s[98:99]
	global_store_dwordx4 v[100:101], v[96:99], off
	s_nop 1
	v_fmamk_f32 v97, v153, 0x3a800000, v227
	s_nop 0
	v_rsq_f32_e32 v97, v97
	s_nop 0
	v_mov_b32_e32 v98, v97
	v_pk_fma_f32 v[92:93], v[92:93], v[98:99], v[246:247] op_sel_hi:[1,0,1]
	v_pk_fma_f32 v[84:85], v[84:85], v[98:99], v[238:239] op_sel_hi:[1,0,1]
	v_mul_f32_e32 v97, 0xbfb8aa3b, v92
	v_exp_f32_e32 v97, v97
	v_pk_fma_f32 v[86:87], v[86:87], v[98:99], v[240:241] op_sel_hi:[1,0,1]
	v_pk_fma_f32 v[88:89], v[88:89], v[98:99], v[242:243] op_sel_hi:[1,0,1]
	v_pk_fma_f32 v[80:81], v[80:81], v[98:99], v[174:175] op_sel_hi:[1,0,1]
	v_add_f32_e32 v97, 1.0, v97
	v_rcp_f32_e32 v100, v97
	v_mul_f32_e32 v97, 0xbfb8aa3b, v93
	v_exp_f32_e32 v97, v97
	v_pk_fma_f32 v[82:83], v[82:83], v[98:99], v[176:177] op_sel_hi:[1,0,1]
	v_add_f32_e32 v97, 1.0, v97
	v_rcp_f32_e32 v101, v97
	s_nop 0
	v_pk_mul_f32 v[92:93], v[92:93], v[100:101]
	s_nop 0
	v_pk_mul_f32 v[84:85], v[84:85], v[92:93]
	v_pk_fma_f32 v[92:93], v[94:95], v[98:99], v[248:249] op_sel_hi:[1,0,1]
	s_nop 0
	v_pk_mul_f32 v[94:95], v[92:93], s[100:101] op_sel_hi:[1,0]
	s_nop 0
	v_exp_f32_e32 v94, v94
	v_exp_f32_e32 v95, v95
	s_nop 0
	v_pk_add_f32 v[94:95], v[94:95], 1.0 op_sel_hi:[1,0]
	s_nop 0
	v_rcp_f32_e32 v94, v94
	v_rcp_f32_e32 v95, v95
	s_nop 0
	v_pk_mul_f32 v[92:93], v[92:93], v[94:95]
	s_nop 0
	v_pk_mul_f32 v[86:87], v[86:87], v[92:93]
	v_pk_mul_f32 v[92:93], v[88:89], s[100:101] op_sel_hi:[1,0]
	s_nop 0
	v_exp_f32_e32 v92, v92
	v_exp_f32_e32 v93, v93
	s_nop 0
	v_pk_add_f32 v[92:93], v[92:93], 1.0 op_sel_hi:[1,0]
	s_nop 0
	v_rcp_f32_e32 v92, v92
	v_rcp_f32_e32 v93, v93
	s_nop 0
	v_pk_mul_f32 v[88:89], v[88:89], v[92:93]
	s_nop 0
	v_pk_mul_f32 v[88:89], v[80:81], v[88:89]
	v_pk_fma_f32 v[80:81], v[90:91], v[98:99], v[244:245] op_sel_hi:[1,0,1]
	s_nop 0
	v_pk_mul_f32 v[90:91], v[80:81], s[100:101] op_sel_hi:[1,0]
	s_nop 0
	v_exp_f32_e32 v90, v90
	v_exp_f32_e32 v91, v91
	s_nop 0
	v_pk_add_f32 v[90:91], v[90:91], 1.0 op_sel_hi:[1,0]
	s_nop 0
	v_rcp_f32_e32 v90, v90
	v_rcp_f32_e32 v91, v91
	s_nop 0
	v_pk_mul_f32 v[80:81], v[80:81], v[90:91]
	s_nop 0
	v_pk_mul_f32 v[90:91], v[82:83], v[80:81]
	v_cvt_pk_bf16_f32 v80, v84, v85
	s_mov_b32 s98, 0x42000
	v_cvt_pk_bf16_f32 v81, v86, v87
	v_cvt_pk_bf16_f32 v82, v88, v89
	v_cvt_pk_bf16_f32 v83, v90, v91
	v_lshl_add_u64 v[84:85], v[194:195], 0, s[98:99]
	global_store_dwordx4 v[84:85], v[80:83], off
	s_nop 0
	s_nop 0
	v_fmamk_f32 v80, v155, 0x3a800000, v227
	s_nop 0
	v_rsq_f32_e32 v80, v80
	s_nop 0
	v_pk_fma_f32 v[76:77], v[76:77], v[80:81], v[246:247] op_sel_hi:[1,0,1]
	v_pk_fma_f32 v[68:69], v[68:69], v[80:81], v[238:239] op_sel_hi:[1,0,1]
	v_pk_mul_f32 v[82:83], v[76:77], s[100:101] op_sel_hi:[1,0]
	s_nop 0
	v_exp_f32_e32 v82, v82
	v_exp_f32_e32 v83, v83
	v_pk_fma_f32 v[70:71], v[70:71], v[80:81], v[240:241] op_sel_hi:[1,0,1]
	v_pk_fma_f32 v[72:73], v[72:73], v[80:81], v[242:243] op_sel_hi:[1,0,1]
	v_pk_add_f32 v[82:83], v[82:83], 1.0 op_sel_hi:[1,0]
	s_nop 0
	v_rcp_f32_e32 v82, v82
	v_rcp_f32_e32 v83, v83
	v_pk_fma_f32 v[64:65], v[64:65], v[80:81], v[174:175] op_sel_hi:[1,0,1]
; __device__ __forceinline__ unsigned pk_bf16(float lo, float hi) { f32x2 v = {lo, hi}; bf16x2_t b = __builtin_convertvector(v, bf16x2_t); return __builtin_bit_cast(unsigned, b); }
;     __device__ __forceinline__ void operator()(const f32x4 (&acc)[2][2][4][2], const Unit& u, int wr, int wc, int fr, int fq) const {
;     ...
;             for (int m = 0; m < 4; ++m) {
;                 float o[8]; const float rv = rsqrtf(rowss[row0 + ai * HALF + m * 16] * (1.0f / 1024.0f) + 1e-6f);
; #pragma unroll
;                 for (int n = 0; n < 2; ++n)
; #pragma unroll
;                     for (int j = 0; j < 4; ++j) { const float g = acc[ai][0][m][n][j] * rv + bz[0][n][j], up = acc[ai][1][m][n][j] * rv + bz[1][n][j];
;                         o[4 * n + j] = g * __builtin_amdgcn_rcpf(1.0f + __expf(-g)) * up; }
;                 u32x4 w; w.x = pk_bf16(o[0], o[1]); w.y = pk_bf16(o[2], o[3]); w.z = pk_bf16(o[4], o[5]); w.w = pk_bf16(o[6], o[7]);
;                 *(u32x4*)(act + (size_t)(row0 + ai * HALF + m * 16) * 2816 + col0) = w;
	v_pk_fma_f32 v[66:67], v[66:67], v[80:81], v[176:177] op_sel_hi:[1,0,1]
	v_pk_mul_f32 v[76:77], v[76:77], v[82:83]
	s_nop 0
	v_pk_mul_f32 v[68:69], v[68:69], v[76:77]
	v_pk_fma_f32 v[76:77], v[78:79], v[80:81], v[248:249] op_sel_hi:[1,0,1]
	s_nop 0
	v_pk_mul_f32 v[78:79], v[76:77], s[100:101] op_sel_hi:[1,0]
	s_nop 0
	v_exp_f32_e32 v78, v78
	v_exp_f32_e32 v79, v79
	s_nop 0
	v_pk_add_f32 v[78:79], v[78:79], 1.0 op_sel_hi:[1,0]
	s_nop 0
	v_rcp_f32_e32 v78, v78
	v_rcp_f32_e32 v79, v79
	s_nop 0
	v_pk_mul_f32 v[76:77], v[76:77], v[78:79]
	s_nop 0
	v_pk_mul_f32 v[70:71], v[70:71], v[76:77]
	v_pk_mul_f32 v[76:77], v[72:73], s[100:101] op_sel_hi:[1,0]
	s_nop 0
	v_exp_f32_e32 v76, v76
	v_exp_f32_e32 v77, v77
	s_nop 0
	v_pk_add_f32 v[76:77], v[76:77], 1.0 op_sel_hi:[1,0]
	s_nop 0
	v_rcp_f32_e32 v76, v76
	v_rcp_f32_e32 v77, v77
	s_nop 0
	v_pk_mul_f32 v[72:73], v[72:73], v[76:77]
	s_nop 0
	v_pk_mul_f32 v[72:73], v[64:65], v[72:73]
	v_pk_fma_f32 v[64:65], v[74:75], v[80:81], v[244:245] op_sel_hi:[1,0,1]
	s_nop 0
	v_pk_mul_f32 v[74:75], v[64:65], s[100:101] op_sel_hi:[1,0]
	s_nop 0
	v_exp_f32_e32 v74, v74
	v_exp_f32_e32 v75, v75
	s_nop 0
	v_pk_add_f32 v[74:75], v[74:75], 1.0 op_sel_hi:[1,0]
	s_nop 0
	v_rcp_f32_e32 v74, v74
	v_rcp_f32_e32 v75, v75
	s_nop 0
	v_pk_mul_f32 v[64:65], v[64:65], v[74:75]
	s_nop 0
	v_pk_mul_f32 v[74:75], v[66:67], v[64:65]
	v_cvt_pk_bf16_f32 v64, v68, v69
	s_mov_b32 s98, 0xb0000
	v_cvt_pk_bf16_f32 v65, v70, v71
	v_cvt_pk_bf16_f32 v66, v72, v73
	v_cvt_pk_bf16_f32 v67, v74, v75
	v_lshl_add_u64 v[68:69], v[194:195], 0, s[98:99]
	global_store_dwordx4 v[68:69], v[64:67], off
	s_nop 0
	s_nop 0
	v_fmamk_f32 v64, v167, 0x3a800000, v227
	s_nop 0
	v_rsq_f32_e32 v64, v64
	s_nop 0
	v_pk_fma_f32 v[60:61], v[60:61], v[64:65], v[246:247] op_sel_hi:[1,0,1]
	v_pk_fma_f32 v[52:53], v[52:53], v[64:65], v[238:239] op_sel_hi:[1,0,1]
	v_pk_mul_f32 v[66:67], v[60:61], s[100:101] op_sel_hi:[1,0]
	s_nop 0
	v_exp_f32_e32 v66, v66
	v_exp_f32_e32 v67, v67
	v_pk_fma_f32 v[54:55], v[54:55], v[64:65], v[240:241] op_sel_hi:[1,0,1]
	v_pk_fma_f32 v[56:57], v[56:57], v[64:65], v[242:243] op_sel_hi:[1,0,1]
	v_pk_add_f32 v[66:67], v[66:67], 1.0 op_sel_hi:[1,0]
	s_nop 0
	v_rcp_f32_e32 v66, v66
	v_rcp_f32_e32 v67, v67
	v_pk_fma_f32 v[48:49], v[48:49], v[64:65], v[174:175] op_sel_hi:[1,0,1]
	v_pk_fma_f32 v[50:51], v[50:51], v[64:65], v[176:177] op_sel_hi:[1,0,1]
	v_pk_mul_f32 v[60:61], v[60:61], v[66:67]
	s_nop 0
	v_pk_mul_f32 v[52:53], v[52:53], v[60:61]
	v_pk_fma_f32 v[60:61], v[62:63], v[64:65], v[248:249] op_sel_hi:[1,0,1]
	s_nop 0
	v_pk_mul_f32 v[62:63], v[60:61], s[100:101] op_sel_hi:[1,0]
	s_nop 0
	v_exp_f32_e32 v62, v62
	v_exp_f32_e32 v63, v63
	s_nop 0
	v_pk_add_f32 v[62:63], v[62:63], 1.0 op_sel_hi:[1,0]
	s_nop 0
	v_rcp_f32_e32 v62, v62
	v_rcp_f32_e32 v63, v63
	s_nop 0
	v_pk_mul_f32 v[60:61], v[60:61], v[62:63]
	s_nop 0
	v_pk_mul_f32 v[54:55], v[54:55], v[60:61]
	v_pk_mul_f32 v[60:61], v[56:57], s[100:101] op_sel_hi:[1,0]
	s_nop 0
	v_exp_f32_e32 v60, v60
	v_exp_f32_e32 v61, v61
	s_nop 0
	v_pk_add_f32 v[60:61], v[60:61], 1.0 op_sel_hi:[1,0]
	s_nop 0
	v_rcp_f32_e32 v60, v60
	v_rcp_f32_e32 v61, v61
	s_nop 0
	v_pk_mul_f32 v[56:57], v[56:57], v[60:61]
	s_nop 0
	v_pk_mul_f32 v[56:57], v[48:49], v[56:57]
	v_pk_fma_f32 v[48:49], v[58:59], v[64:65], v[244:245] op_sel_hi:[1,0,1]
	s_nop 0
	v_pk_mul_f32 v[58:59], v[48:49], s[100:101] op_sel_hi:[1,0]
	s_nop 0
	v_exp_f32_e32 v58, v58
	v_exp_f32_e32 v59, v59
	s_nop 0
	v_pk_add_f32 v[58:59], v[58:59], 1.0 op_sel_hi:[1,0]
	s_nop 0
	v_rcp_f32_e32 v58, v58
	v_rcp_f32_e32 v59, v59
	s_nop 0
	v_pk_mul_f32 v[48:49], v[48:49], v[58:59]
	s_nop 0
	v_pk_mul_f32 v[58:59], v[50:51], v[48:49]
	v_cvt_pk_bf16_f32 v48, v52, v53
	s_mov_b32 s98, 0xc6000
	v_cvt_pk_bf16_f32 v49, v54, v55
	v_cvt_pk_bf16_f32 v50, v56, v57
	v_cvt_pk_bf16_f32 v51, v58, v59
	v_lshl_add_u64 v[52:53], v[194:195], 0, s[98:99]
	global_store_dwordx4 v[52:53], v[48:51], off
	s_nop 0
	s_nop 0
	v_fmamk_f32 v48, v173, 0x3a800000, v227
	s_nop 0
	v_rsq_f32_e32 v48, v48
	s_nop 0
	v_pk_fma_f32 v[28:29], v[28:29], v[48:49], v[246:247] op_sel_hi:[1,0,1]
	v_pk_fma_f32 v[20:21], v[20:21], v[48:49], v[238:239] op_sel_hi:[1,0,1]
	v_pk_mul_f32 v[50:51], v[28:29], s[100:101] op_sel_hi:[1,0]
	s_nop 0
	v_exp_f32_e32 v50, v50
	v_exp_f32_e32 v51, v51
; __device__ __forceinline__ unsigned pk_bf16(float lo, float hi) { f32x2 v = {lo, hi}; bf16x2_t b = __builtin_convertvector(v, bf16x2_t); return __builtin_bit_cast(unsigned, b); }
;     __device__ __forceinline__ void operator()(const f32x4 (&acc)[2][2][4][2], const Unit& u, int wr, int wc, int fr, int fq) const {
;     ...
;             for (int m = 0; m < 4; ++m) {
;                 float o[8]; const float rv = rsqrtf(rowss[row0 + ai * HALF + m * 16] * (1.0f / 1024.0f) + 1e-6f);
; #pragma unroll
;                 for (int n = 0; n < 2; ++n)
; #pragma unroll
;                     for (int j = 0; j < 4; ++j) { const float g = acc[ai][0][m][n][j] * rv + bz[0][n][j], up = acc[ai][1][m][n][j] * rv + bz[1][n][j];
;                         o[4 * n + j] = g * __builtin_amdgcn_rcpf(1.0f + __expf(-g)) * up; }
;                 u32x4 w; w.x = pk_bf16(o[0], o[1]); w.y = pk_bf16(o[2], o[3]); w.z = pk_bf16(o[4], o[5]); w.w = pk_bf16(o[6], o[7]);
;                 *(u32x4*)(act + (size_t)(row0 + ai * HALF + m * 16) * 2816 + col0) = w;
; template <class Epi, class Sched, bool ALIGN_EPI = false, bool SP2 = false, bool F16 = false>
; __device__ __forceinline__ void gemm_phase(PG8_LAS unsigned char* lds, const Gemm g, const Sched& S, const Epi& E) {
;     ...
;         if (!has_next) break;
	v_pk_fma_f32 v[22:23], v[22:23], v[48:49], v[240:241] op_sel_hi:[1,0,1]
	v_pk_fma_f32 v[24:25], v[24:25], v[48:49], v[242:243] op_sel_hi:[1,0,1]
	v_pk_add_f32 v[50:51], v[50:51], 1.0 op_sel_hi:[1,0]
	s_nop 0
	v_rcp_f32_e32 v50, v50
	v_rcp_f32_e32 v51, v51
	v_pk_fma_f32 v[16:17], v[16:17], v[48:49], v[174:175] op_sel_hi:[1,0,1]
	v_pk_fma_f32 v[18:19], v[18:19], v[48:49], v[176:177] op_sel_hi:[1,0,1]
	v_pk_mul_f32 v[28:29], v[28:29], v[50:51]
	s_nop 0
	v_pk_mul_f32 v[20:21], v[20:21], v[28:29]
	v_pk_fma_f32 v[28:29], v[30:31], v[48:49], v[248:249] op_sel_hi:[1,0,1]
	s_nop 0
	v_pk_mul_f32 v[30:31], v[28:29], s[100:101] op_sel_hi:[1,0]
	s_nop 0
	v_exp_f32_e32 v30, v30
	v_exp_f32_e32 v31, v31
	s_nop 0
	v_pk_add_f32 v[30:31], v[30:31], 1.0 op_sel_hi:[1,0]
	s_nop 0
	v_rcp_f32_e32 v30, v30
	v_rcp_f32_e32 v31, v31
	s_nop 0
	v_pk_mul_f32 v[28:29], v[28:29], v[30:31]
	s_nop 0
	v_pk_mul_f32 v[22:23], v[22:23], v[28:29]
	v_pk_mul_f32 v[28:29], v[24:25], s[100:101] op_sel_hi:[1,0]
	s_nop 0
	v_exp_f32_e32 v28, v28
	v_exp_f32_e32 v29, v29
	s_nop 0
	v_pk_add_f32 v[28:29], v[28:29], 1.0 op_sel_hi:[1,0]
	s_nop 0
	v_rcp_f32_e32 v28, v28
	v_rcp_f32_e32 v29, v29
	s_nop 0
	v_pk_mul_f32 v[24:25], v[24:25], v[28:29]
	s_nop 0
	v_pk_mul_f32 v[24:25], v[16:17], v[24:25]
	v_pk_fma_f32 v[16:17], v[26:27], v[48:49], v[244:245] op_sel_hi:[1,0,1]
	s_nop 0
	v_pk_mul_f32 v[26:27], v[16:17], s[100:101] op_sel_hi:[1,0]
	s_nop 0
	v_exp_f32_e32 v26, v26
	v_exp_f32_e32 v27, v27
	s_nop 0
	v_pk_add_f32 v[26:27], v[26:27], 1.0 op_sel_hi:[1,0]
	s_nop 0
	v_rcp_f32_e32 v26, v26
	v_rcp_f32_e32 v27, v27
	s_nop 0
	v_pk_mul_f32 v[16:17], v[16:17], v[26:27]
	s_nop 0
	v_pk_mul_f32 v[26:27], v[18:19], v[16:17]
	v_cvt_pk_bf16_f32 v16, v20, v21
	s_mov_b32 s98, 0xdc000
	v_cvt_pk_bf16_f32 v17, v22, v23
	v_cvt_pk_bf16_f32 v18, v24, v25
	v_cvt_pk_bf16_f32 v19, v26, v27
	v_lshl_add_u64 v[20:21], v[194:195], 0, s[98:99]
	global_store_dwordx4 v[20:21], v[16:19], off
	s_nop 0
	s_nop 0
	v_fmamk_f32 v16, v250, 0x3a800000, v227
	s_nop 0
	v_rsq_f32_e32 v16, v16
	s_nop 0
	v_pk_fma_f32 v[12:13], v[12:13], v[16:17], v[246:247] op_sel_hi:[1,0,1]
	v_pk_fma_f32 v[4:5], v[4:5], v[16:17], v[238:239] op_sel_hi:[1,0,1]
	v_pk_mul_f32 v[18:19], v[12:13], s[100:101] op_sel_hi:[1,0]
	s_nop 0
	v_exp_f32_e32 v18, v18
	v_exp_f32_e32 v19, v19
	v_pk_fma_f32 v[6:7], v[6:7], v[16:17], v[240:241] op_sel_hi:[1,0,1]
	v_pk_fma_f32 v[8:9], v[8:9], v[16:17], v[242:243] op_sel_hi:[1,0,1]
	v_pk_add_f32 v[18:19], v[18:19], 1.0 op_sel_hi:[1,0]
	s_nop 0
	v_rcp_f32_e32 v18, v18
	v_rcp_f32_e32 v19, v19
	v_pk_fma_f32 v[0:1], v[0:1], v[16:17], v[174:175] op_sel_hi:[1,0,1]
	v_pk_fma_f32 v[2:3], v[2:3], v[16:17], v[176:177] op_sel_hi:[1,0,1]
	s_andn2_b64 vcc, exec, s[40:41]
	v_pk_mul_f32 v[12:13], v[12:13], v[18:19]
	s_nop 0
	v_pk_mul_f32 v[4:5], v[4:5], v[12:13]
	v_pk_fma_f32 v[12:13], v[14:15], v[16:17], v[248:249] op_sel_hi:[1,0,1]
	s_nop 0
	v_pk_mul_f32 v[14:15], v[12:13], s[100:101] op_sel_hi:[1,0]
	s_nop 0
	v_exp_f32_e32 v14, v14
	v_exp_f32_e32 v15, v15
	s_nop 0
	v_pk_add_f32 v[14:15], v[14:15], 1.0 op_sel_hi:[1,0]
	s_nop 0
	v_rcp_f32_e32 v14, v14
	v_rcp_f32_e32 v15, v15
	s_nop 0
	v_pk_mul_f32 v[12:13], v[12:13], v[14:15]
	s_nop 0
	v_pk_mul_f32 v[6:7], v[6:7], v[12:13]
	v_pk_mul_f32 v[12:13], v[8:9], s[100:101] op_sel_hi:[1,0]
	s_nop 0
	v_exp_f32_e32 v12, v12
	v_exp_f32_e32 v13, v13
	s_nop 0
	v_pk_add_f32 v[12:13], v[12:13], 1.0 op_sel_hi:[1,0]
	s_nop 0
	v_rcp_f32_e32 v12, v12
	v_rcp_f32_e32 v13, v13
	s_nop 0
	v_pk_mul_f32 v[8:9], v[8:9], v[12:13]
	s_nop 0
	v_pk_mul_f32 v[8:9], v[0:1], v[8:9]
	v_pk_fma_f32 v[0:1], v[10:11], v[16:17], v[244:245] op_sel_hi:[1,0,1]
	s_nop 0
	v_pk_mul_f32 v[10:11], v[0:1], s[100:101] op_sel_hi:[1,0]
	s_nop 0
	v_exp_f32_e32 v10, v10
	v_exp_f32_e32 v11, v11
	s_nop 0
	v_pk_add_f32 v[10:11], v[10:11], 1.0 op_sel_hi:[1,0]
	s_nop 0
	v_rcp_f32_e32 v10, v10
	v_rcp_f32_e32 v11, v11
	s_nop 0
	v_pk_mul_f32 v[0:1], v[0:1], v[10:11]
	s_nop 0
	v_pk_mul_f32 v[10:11], v[2:3], v[0:1]
	v_cvt_pk_bf16_f32 v0, v4, v5
	s_mov_b32 s98, 0xf2000
	v_cvt_pk_bf16_f32 v1, v6, v7
	v_cvt_pk_bf16_f32 v2, v8, v9
	v_cvt_pk_bf16_f32 v3, v10, v11
	v_lshl_add_u64 v[4:5], v[194:195], 0, s[98:99]
	global_store_dwordx4 v[4:5], v[0:3], off
	s_cbranch_vccnz .LBB0_900
	s_andn2_b64 vcc, exec, s[0:1]
	s_cbranch_vccnz .LBB0_899
	s_barrier
	s_branch .LBB0_899
